# rstd prepass: when consecutive units of a workgroup share the same row-panel (pm), reuse the rstd value from the previous iteration instead of re-loading and recomputing it
# speedup vs baseline: 1.0029x; 1.0029x over previous
.LBB0_396:
	s_mov_b32 s6, -1
	s_waitcnt lgkmcnt(0)
	s_add_u32 s4, s0, 0x51a00000
	v_mbcnt_lo_u32_b32 v0, s6, 0
	v_mbcnt_hi_u32_b32 v0, s6, v0
	v_and_b32_e32 v4, 1, v0
	v_add_u32_e32 v2, s2, v0
	v_lshlrev_b32_e32 v0, 6, v4
	s_addc_u32 s5, s1, 0
	v_ashrrev_i32_e32 v6, 1, v2
	v_lshl_add_u64 v[2:3], s[0:1], 0, v[0:1]
	s_mov_b64 s[6:7], 0x5ba00000
	s_add_i32 s8, 0, 0x201c0
	v_lshl_add_u64 v[2:3], v[2:3], 0, s[6:7]
	v_cmp_eq_u32_e64 s[6:7], 0, v4
	v_lshl_add_u32 v0, v6, 2, s8
	s_mov_b64 s[10:11], s[80:81]
	s_mov_b32 s86, -1
	s_branch .LBB0_399

.LBB0_399:
	v_mov_b64_e32 v[4:5], 0xaff
	v_cmp_gt_i64_e32 vcc, s[10:11], v[4:5]
	s_mov_b64 s[8:9], -1
	s_cbranch_vccnz .LBB0_398
	s_ashr_i32 s8, s10, 31
	s_lshr_b32 s8, s8, 29
	s_add_i32 s8, s10, s8
	s_ashr_i32 s9, s8, 3
	s_and_b32 s8, s8, -8
	s_sub_i32 s8, s10, s8
	s_cmp_lt_i32 s8, 0
	s_movk_i32 s3, 0x161
	s_cselect_b32 s12, s3, 0x160
	s_mul_i32 s8, s8, s12
	s_add_i32 s8, s8, s9
	s_mul_hi_i32 s9, s8, 0x2e8ba2e9
	s_lshr_b32 s12, s9, 31
	s_ashr_i32 s9, s9, 5
	s_add_i32 s9, s9, s12
	s_lshl_b32 s12, s9, 2
	s_sub_i32 s13, 64, s12
	s_min_i32 s13, s13, 4
	s_abs_i32 s13, s13
	v_cvt_f32_u32_e32 v4, s13
	s_sub_i32 s14, 0, s13
	s_mulk_i32 s9, 0xb0
	s_sub_i32 s8, s8, s9
	v_rcp_iflag_f32_e32 v4, v4
	s_ashr_i32 s9, s8, 31
	s_abs_i32 s8, s8
	v_xor_b32_e32 v7, 1, v216
	v_mul_f32_e32 v4, 0x4f7ffffe, v4
	v_cvt_u32_f32_e32 v4, v4
	v_cmp_lt_i32_e32 vcc, v7, v217
	v_readfirstlane_b32 s15, v4
	s_mul_i32 s14, s14, s15
	s_mul_hi_u32 s14, s15, s14
	s_add_i32 s15, s15, s14
	s_mul_hi_u32 s14, s8, s15
	s_mul_i32 s14, s14, s13
	s_sub_i32 s8, s8, s14
	s_sub_i32 s14, s8, s13
	s_cmp_ge_u32 s8, s13
	s_cselect_b32 s8, s14, s8
	s_sub_i32 s14, s8, s13
	s_cmp_ge_u32 s8, s13
	s_cselect_b32 s8, s14, s8
	s_xor_b32 s8, s8, s9
	s_sub_i32 s8, s8, s9
	s_add_i32 s12, s12, s8
	s_cmp_eq_u32 s12, s86
	s_cbranch_scc1 .Lmy_rsame_0
	s_mov_b32 s86, s12
	v_lshl_add_u32 v4, s12, 8, v6
	v_ashrrev_i32_e32 v5, 31, v4
	s_waitcnt lgkmcnt(0)
	v_lshlrev_b64 v[8:9], 7, v[4:5]
	v_lshl_add_u64 v[248:249], v[4:5], 2, s[4:5]
	global_load_dword v250, v[248:249], off
	v_lshl_add_u64 v[20:21], v[2:3], 0, v[8:9]
	global_load_dwordx4 v[8:11], v[20:21], off
	global_load_dwordx4 v[12:15], v[20:21], off offset:16
	global_load_dwordx4 v[16:19], v[20:21], off offset:32
	s_nop 0
	global_load_dwordx4 v[20:23], v[20:21], off offset:48
	v_cndmask_b32_e32 v24, v216, v7, vcc
	s_waitcnt vmcnt(0)
	v_add_f32_e32 v7, v8, v9
	v_add_f32_e32 v8, v10, v11
	s_waitcnt vmcnt(2)
	v_add_f32_e32 v9, v12, v13
	v_add_f32_e32 v10, v14, v15
	s_waitcnt vmcnt(1)
	v_add_f32_e32 v11, v16, v17
	v_add_f32_e32 v12, v18, v19
	s_waitcnt vmcnt(0)
	v_add_f32_e32 v13, v20, v21
	v_add_f32_e32 v14, v22, v23
	v_add_f32_e32 v7, v7, v8
	v_add_f32_e32 v8, v9, v10
	v_add_f32_e32 v9, v11, v12
	v_add_f32_e32 v10, v13, v14
	v_add_f32_e32 v7, v7, v8
	v_add_f32_e32 v8, v9, v10
	v_add_f32_e32 v7, v7, v8
	v_lshlrev_b32_e32 v8, 2, v24
	ds_bpermute_b32 v8, v8, v7
	s_and_saveexec_b64 s[12:13], s[6:7]
	s_cbranch_execz .LBB0_397
	s_waitcnt lgkmcnt(0)
	v_add_f32_e32 v5, v7, v8
	v_fmamk_f32 v5, v5, 0x3a000000, v156
	s_mov_b32 s3, 0xf800000
	v_mul_f32_e32 v7, 0x4f800000, v5
	v_cmp_gt_f32_e32 vcc, s3, v5
	s_nop 1
	v_cndmask_b32_e32 v5, v5, v7, vcc
	v_sqrt_f32_e32 v7, v5
	s_nop 0
	v_add_u32_e32 v8, -1, v7
	v_fma_f32 v9, -v8, v7, v5
	v_cmp_ge_f32_e64 s[8:9], 0, v9
	v_add_u32_e32 v9, 1, v7
	s_nop 0
	v_cndmask_b32_e64 v8, v7, v8, s[8:9]
	v_fma_f32 v7, -v9, v7, v5
	v_cmp_lt_f32_e64 s[8:9], 0, v7
	s_nop 1
	v_cndmask_b32_e64 v7, v8, v9, s[8:9]
	v_mul_f32_e32 v8, 0x37800000, v7
	v_cndmask_b32_e32 v7, v7, v8, vcc
	v_cmp_class_f32_e32 vcc, v5, v157
	s_nop 1
	v_cndmask_b32_e32 v5, v7, v5, vcc
	v_div_scale_f32 v7, s[8:9], v5, v5, 1.0
	v_rcp_f32_e32 v8, v7
	s_nop 0
	v_fma_f32 v9, -v7, v8, 1.0
	v_fmac_f32_e32 v8, v9, v8
	v_div_scale_f32 v9, vcc, 1.0, v5, 1.0
	v_mul_f32_e32 v10, v9, v8
	v_fma_f32 v11, -v7, v10, v9
	v_fmac_f32_e32 v10, v11, v8
	v_fma_f32 v7, -v7, v10, v9
	v_div_fmas_f32 v7, v7, v8, v10
	v_div_fixup_f32 v5, v7, v5, 1.0
	s_waitcnt vmcnt(0)
	v_mul_f32_e32 v4, v5, v250
	v_mov_b32_e32 v100, v4
	ds_write_b32 v0, v4
	s_branch .LBB0_397
.Lmy_rsame_0:
	s_and_saveexec_b64 s[12:13], s[6:7]
	ds_write_b32 v0, v100
	s_branch .LBB0_397

.LBB0_595:
	s_add_i32 s0, s0, s80
	s_bitcmp1_b32 s0, 0
	s_cselect_b64 s[0:1], -1, 0
	s_and_b64 vcc, exec, s[0:1]
	s_mov_b64 s[0:1], -1
	s_cbranch_vccz .LBB0_649
	v_readlane_b32 s0, v251, 2
	v_readlane_b32 s4, v254, 51
	v_readlane_b32 s1, v251, 3
	v_readlane_b32 s6, v254, 53
	v_readlane_b32 s18, v254, 55
	s_mov_b32 s4, s6
	s_load_dwordx2 s[0:1], s[0:1], 0xb8
	s_mov_b32 s6, -1
	v_readlane_b32 s7, v254, 54
	v_mbcnt_lo_u32_b32 v0, s6, 0
	v_mbcnt_hi_u32_b32 v0, s6, v0
	v_and_b32_e32 v4, 1, v0
	v_add_u32_e32 v2, s2, v0
	v_lshlrev_b32_e32 v0, 6, v4
	v_readlane_b32 s5, v254, 52
	s_waitcnt lgkmcnt(0)
	s_add_u32 s4, s0, 0x51a00000
	v_ashrrev_i32_e32 v6, 1, v2
	v_lshl_add_u64 v[2:3], s[0:1], 0, v[0:1]
	s_mov_b64 s[6:7], 0x5ba00000
	s_addc_u32 s5, s1, 0
	v_lshl_add_u64 v[2:3], v[2:3], 0, s[6:7]
	s_add_i32 s6, 0, 0x219c0
	s_mov_b32 s19, 0
	v_cmp_eq_u32_e64 s[8:9], 0, v4
	v_lshl_add_u32 v0, v6, 2, s6
	s_mov_b64 s[14:15], s[80:81]
	s_mov_b32 s20, s80
	s_mov_b32 s86, -1
	s_branch .LBB0_599

.LBB0_614:
	s_mov_b64 s[16:17], -1
	s_and_b64 vcc, exec, s[10:11]
	s_cbranch_vccz .LBB0_598
	s_ashr_i32 s10, s22, 31
	s_lshr_b32 s10, s10, 29
	s_add_i32 s10, s22, s10
	s_ashr_i32 s10, s10, 3
	s_add_i32 s10, s21, s10
	s_mul_hi_i32 s11, s10, 0x2aaaaaab
	s_lshr_b32 s16, s11, 31
	s_ashr_i32 s11, s11, 4
	s_add_i32 s11, s11, s16
	s_lshl_b32 s16, s11, 2
	s_sub_i32 s17, 64, s16
	s_min_i32 s17, s17, 4
	s_abs_i32 s17, s17
	v_cvt_f32_u32_e32 v4, s17
	s_sub_i32 s21, 0, s17
	s_mulk_i32 s11, 0x60
	s_sub_i32 s10, s10, s11
	v_rcp_iflag_f32_e32 v4, v4
	s_ashr_i32 s11, s10, 31
	s_abs_i32 s10, s10
	v_xor_b32_e32 v7, 1, v216
	v_mul_f32_e32 v4, 0x4f7ffffe, v4
	v_cvt_u32_f32_e32 v4, v4
	v_cmp_lt_i32_e32 vcc, v7, v217
	v_readfirstlane_b32 s22, v4
	s_mul_i32 s21, s21, s22
	s_mul_hi_u32 s21, s22, s21
	s_add_i32 s22, s22, s21
	s_mul_hi_u32 s21, s10, s22
	s_mul_i32 s21, s21, s17
	s_sub_i32 s10, s10, s21
	s_sub_i32 s21, s10, s17
	s_cmp_ge_u32 s10, s17
	s_cselect_b32 s10, s21, s10
	s_sub_i32 s21, s10, s17
	s_cmp_ge_u32 s10, s17
	s_cselect_b32 s10, s21, s10
	s_xor_b32 s10, s10, s11
	s_sub_i32 s10, s10, s11
	s_add_i32 s16, s16, s10
	s_cmp_eq_u32 s16, s86
	s_cbranch_scc1 .Lmy_rsame_1
	s_mov_b32 s86, s16
	v_lshl_add_u32 v4, s16, 8, v6
	v_ashrrev_i32_e32 v5, 31, v4
	s_waitcnt lgkmcnt(0)
	v_lshlrev_b64 v[8:9], 7, v[4:5]
	v_lshl_add_u64 v[248:249], v[4:5], 2, s[4:5]
	global_load_dword v250, v[248:249], off
	v_lshl_add_u64 v[20:21], v[2:3], 0, v[8:9]
	global_load_dwordx4 v[8:11], v[20:21], off
	global_load_dwordx4 v[12:15], v[20:21], off offset:16
	global_load_dwordx4 v[16:19], v[20:21], off offset:32
	s_nop 0
	global_load_dwordx4 v[20:23], v[20:21], off offset:48
	v_cndmask_b32_e32 v24, v216, v7, vcc
	s_waitcnt vmcnt(0)
	v_add_f32_e32 v7, v8, v9
	v_add_f32_e32 v8, v10, v11
	s_waitcnt vmcnt(2)
	v_add_f32_e32 v9, v12, v13
	v_add_f32_e32 v10, v14, v15
	s_waitcnt vmcnt(1)
	v_add_f32_e32 v11, v16, v17
	v_add_f32_e32 v12, v18, v19
	s_waitcnt vmcnt(0)
	v_add_f32_e32 v13, v20, v21
	v_add_f32_e32 v14, v22, v23
	v_add_f32_e32 v7, v7, v8
	v_add_f32_e32 v8, v9, v10
	v_add_f32_e32 v9, v11, v12
	v_add_f32_e32 v10, v13, v14
	v_add_f32_e32 v7, v7, v8
	v_add_f32_e32 v8, v9, v10
	v_add_f32_e32 v7, v7, v8
	v_lshlrev_b32_e32 v8, 2, v24
	ds_bpermute_b32 v8, v8, v7
	s_and_saveexec_b64 s[16:17], s[8:9]
	s_cbranch_execz .LBB0_597
	s_waitcnt lgkmcnt(0)
	v_add_f32_e32 v7, v7, v8
	v_fmamk_f32 v7, v7, 0x3a000000, v156
	s_mov_b32 s3, 0xf800000
	v_cmp_gt_f32_e32 vcc, s3, v7
	v_mul_f32_e32 v8, 0x4f800000, v7
	s_nop 0
	v_cndmask_b32_e32 v7, v7, v8, vcc
	v_sqrt_f32_e32 v8, v7
	s_nop 0
	v_add_u32_e32 v9, -1, v8
	v_fma_f32 v10, -v9, v8, v7
	v_cmp_ge_f32_e64 s[10:11], 0, v10
	v_add_u32_e32 v10, 1, v8
	s_nop 0
	v_cndmask_b32_e64 v9, v8, v9, s[10:11]
	v_fma_f32 v8, -v10, v8, v7
	v_cmp_lt_f32_e64 s[10:11], 0, v8
	s_nop 1
	v_cndmask_b32_e64 v8, v9, v10, s[10:11]
	v_mul_f32_e32 v9, 0x37800000, v8
	v_cndmask_b32_e32 v8, v8, v9, vcc
	v_cmp_class_f32_e32 vcc, v7, v157
	s_nop 1
	v_cndmask_b32_e32 v7, v8, v7, vcc
	v_div_scale_f32 v8, s[10:11], v7, v7, 1.0
	v_rcp_f32_e32 v9, v8
	s_nop 0
	v_fma_f32 v10, -v8, v9, 1.0
	v_fmac_f32_e32 v9, v10, v9
	v_div_scale_f32 v10, vcc, 1.0, v7, 1.0
	v_mul_f32_e32 v11, v10, v9
	v_fma_f32 v12, -v8, v11, v10
	v_fmac_f32_e32 v11, v12, v9
	v_fma_f32 v8, -v8, v11, v10
	v_div_fmas_f32 v8, v8, v9, v11
	v_div_fixup_f32 v7, v8, v7, 1.0
	s_waitcnt vmcnt(0)
	v_mul_f32_e32 v4, v7, v250
	v_mov_b32_e32 v100, v4
	ds_write_b32 v0, v4
	s_branch .LBB0_597
.Lmy_rsame_1:
	s_and_saveexec_b64 s[16:17], s[8:9]
	ds_write_b32 v0, v100
	s_branch .LBB0_597

.LBB0_649:
	s_and_b64 vcc, exec, s[0:1]
	s_cbranch_vccz .LBB0_594
	v_readlane_b32 s4, v254, 51
	v_readlane_b32 s0, v251, 2
	v_readlane_b32 s6, v254, 53
	v_readlane_b32 s1, v251, 3
	v_readlane_b32 s14, v254, 55
	s_mov_b32 s4, s6
	v_readlane_b32 s5, v254, 52
	s_load_dwordx2 s[4:5], s[0:1], 0xb8
	s_mov_b32 s0, -1
	v_readlane_b32 s7, v254, 54
	v_mbcnt_lo_u32_b32 v0, s0, 0
	v_mbcnt_hi_u32_b32 v0, s0, v0
	v_and_b32_e32 v5, 1, v0
	v_add_u32_e32 v2, s2, v0
	v_lshlrev_b32_e32 v0, 6, v5
	v_ashrrev_i32_e32 v4, 1, v2
	s_waitcnt lgkmcnt(0)
	v_lshl_add_u64 v[2:3], s[4:5], 0, v[0:1]
	s_mov_b64 s[0:1], 0x5ba00000
	v_lshl_add_u64 v[2:3], v[2:3], 0, s[0:1]
	s_add_i32 s0, 0, 0x201c0
	v_cmp_eq_u32_e64 s[6:7], 0, v5
	v_lshl_add_u32 v0, v4, 2, s0
	s_mov_b64 s[0:1], s[80:81]
	s_mov_b32 s86, -1
	s_branch .LBB0_653

.LBB0_653:
	s_waitcnt lgkmcnt(0)
	v_mov_b64_e32 v[6:7], 0x57f
	v_cmp_gt_i64_e32 vcc, s[0:1], v[6:7]
	s_mov_b64 s[8:9], -1
	s_cbranch_vccnz .LBB0_652
	s_ashr_i32 s8, s0, 31
	s_lshr_b32 s8, s8, 29
	s_add_i32 s8, s0, s8
	s_ashr_i32 s9, s8, 3
	s_and_b32 s8, s8, -8
	s_sub_i32 s8, s0, s8
	s_cmp_lt_i32 s8, 0
	s_movk_i32 s3, 0xb1
	s_cselect_b32 s10, s3, 0xb0
	s_mul_i32 s8, s8, s10
	s_add_i32 s8, s8, s9
	s_mul_hi_i32 s9, s8, 0x2e8ba2e9
	s_lshr_b32 s10, s9, 31
	s_ashr_i32 s9, s9, 4
	s_add_i32 s9, s9, s10
	s_lshl_b32 s10, s9, 2
	s_sub_i32 s11, 64, s10
	s_min_i32 s11, s11, 4
	s_abs_i32 s11, s11
	v_cvt_f32_u32_e32 v5, s11
	s_sub_i32 s15, 0, s11
	s_mulk_i32 s9, 0x58
	s_sub_i32 s8, s8, s9
	v_rcp_iflag_f32_e32 v5, v5
	s_ashr_i32 s9, s8, 31
	s_abs_i32 s8, s8
	v_mul_f32_e32 v5, 0x4f7ffffe, v5
	v_cvt_u32_f32_e32 v5, v5
	s_nop 0
	v_readfirstlane_b32 s16, v5
	s_mul_i32 s15, s15, s16
	s_mul_hi_u32 s15, s16, s15
	s_add_i32 s16, s16, s15
	s_mul_hi_u32 s15, s8, s16
	s_mul_i32 s15, s15, s11
	s_sub_i32 s8, s8, s15
	s_sub_i32 s15, s8, s11
	s_cmp_ge_u32 s8, s11
	s_cselect_b32 s8, s15, s8
	s_sub_i32 s15, s8, s11
	s_cmp_ge_u32 s8, s11
	s_cselect_b32 s8, s15, s8
	s_xor_b32 s8, s8, s9
	s_sub_i32 s8, s8, s9
	s_add_i32 s10, s10, s8
	s_cmp_eq_u32 s10, s86
	s_cbranch_scc1 .Lmy_rsame_2
	s_mov_b32 s86, s10
	v_lshl_add_u32 v6, s10, 8, v4
	v_ashrrev_i32_e32 v7, 31, v6
	v_lshlrev_b64 v[6:7], 7, v[6:7]
	v_lshl_add_u64 v[18:19], v[2:3], 0, v[6:7]
	global_load_dwordx4 v[6:9], v[18:19], off
	global_load_dwordx4 v[10:13], v[18:19], off offset:16
	global_load_dwordx4 v[14:17], v[18:19], off offset:32
	s_nop 0
	global_load_dwordx4 v[18:21], v[18:19], off offset:48
	v_xor_b32_e32 v5, 1, v216
	v_cmp_lt_i32_e32 vcc, v5, v217
	s_nop 1
	v_cndmask_b32_e32 v22, v216, v5, vcc
	s_waitcnt vmcnt(0)
	v_add_f32_e32 v5, v6, v7
	v_add_f32_e32 v6, v8, v9
	s_waitcnt vmcnt(2)
	v_add_f32_e32 v7, v10, v11
	v_add_f32_e32 v8, v12, v13
	s_waitcnt vmcnt(1)
	v_add_f32_e32 v9, v14, v15
	v_add_f32_e32 v10, v16, v17
	s_waitcnt vmcnt(0)
	v_add_f32_e32 v11, v18, v19
	v_add_f32_e32 v12, v20, v21
	v_add_f32_e32 v5, v5, v6
	v_add_f32_e32 v6, v7, v8
	v_add_f32_e32 v7, v9, v10
	v_add_f32_e32 v8, v11, v12
	v_add_f32_e32 v5, v5, v6
	v_add_f32_e32 v6, v7, v8
	v_add_f32_e32 v5, v5, v6
	v_lshlrev_b32_e32 v6, 2, v22
	ds_bpermute_b32 v6, v6, v5
	s_and_saveexec_b64 s[10:11], s[6:7]
	s_cbranch_execz .LBB0_651
	s_waitcnt lgkmcnt(0)
	v_add_f32_e32 v5, v5, v6
	v_fmamk_f32 v5, v5, 0x3a000000, v156
	s_mov_b32 s3, 0xf800000
	v_mul_f32_e32 v6, 0x4f800000, v5
	v_cmp_gt_f32_e32 vcc, s3, v5
	s_nop 1
	v_cndmask_b32_e32 v5, v5, v6, vcc
	v_sqrt_f32_e32 v6, v5
	s_nop 0
	v_add_u32_e32 v7, -1, v6
	v_fma_f32 v9, -v7, v6, v5
	v_add_u32_e32 v8, 1, v6
	v_cmp_ge_f32_e64 s[8:9], 0, v9
	s_nop 1
	v_cndmask_b32_e64 v7, v6, v7, s[8:9]
	v_fma_f32 v6, -v8, v6, v5
	v_cmp_lt_f32_e64 s[8:9], 0, v6
	s_nop 1
	v_cndmask_b32_e64 v6, v7, v8, s[8:9]
	v_mul_f32_e32 v7, 0x37800000, v6
	v_cndmask_b32_e32 v6, v6, v7, vcc
	v_cmp_class_f32_e32 vcc, v5, v157
	s_nop 1
	v_cndmask_b32_e32 v5, v6, v5, vcc
	v_div_scale_f32 v6, s[8:9], v5, v5, 1.0
	v_rcp_f32_e32 v7, v6
	s_nop 0
	v_fma_f32 v8, -v6, v7, 1.0
	v_fmac_f32_e32 v7, v8, v7
	v_div_scale_f32 v8, vcc, 1.0, v5, 1.0
	v_mul_f32_e32 v9, v8, v7
	v_fma_f32 v10, -v6, v9, v8
	v_fmac_f32_e32 v9, v10, v7
	v_fma_f32 v6, -v6, v9, v8
	v_div_fmas_f32 v6, v6, v7, v9
	v_div_fixup_f32 v5, v6, v5, 1.0
	v_mov_b32_e32 v100, v5
	ds_write_b32 v0, v5
	s_branch .LBB0_651
.Lmy_rsame_2:
	s_and_saveexec_b64 s[10:11], s[6:7]
	ds_write_b32 v0, v100
	s_branch .LBB0_651

.LBB0_2094:
	s_mov_b32 s0, s4
	s_cmp_gt_i32 s0, 9
	s_cbranch_scc1 .LBB0_2170
	s_mov_b32 s0, s5
	s_cmp_lt_i32 s0, 10
	s_cbranch_scc1 .LBB0_2170
	v_readlane_b32 s0, v251, 2
	v_readlane_b32 s4, v254, 51
	v_readlane_b32 s1, v251, 3
	v_readlane_b32 s6, v254, 53
	v_readlane_b32 s14, v254, 55
	s_mov_b32 s4, s6
	s_load_dwordx2 s[0:1], s[0:1], 0xb8
	s_mov_b32 s6, -1
	v_readlane_b32 s5, v254, 52
	v_mbcnt_lo_u32_b32 v0, s6, 0
	v_mbcnt_hi_u32_b32 v0, s6, v0
	v_and_b32_e32 v4, 1, v0
	v_readlane_b32 s7, v254, 54
	s_waitcnt lgkmcnt(0)
	s_add_u32 s4, s0, 0x51a00000
	v_add_u32_e32 v2, s2, v0
	v_lshlrev_b32_e32 v0, 6, v4
	s_addc_u32 s5, s1, 0
	v_ashrrev_i32_e32 v6, 1, v2
	v_lshl_add_u64 v[2:3], s[0:1], 0, v[0:1]
	s_mov_b64 s[6:7], 0x5ba00000
	s_add_i32 s8, 0, 0x201c0
	v_lshl_add_u64 v[2:3], v[2:3], 0, s[6:7]
	v_cmp_eq_u32_e64 s[6:7], 0, v4
	v_lshl_add_u32 v0, v6, 2, s8
	s_mov_b64 s[10:11], s[80:81]
	s_mov_b32 s86, -1
	s_branch .LBB0_2099

.LBB0_2099:
	v_mov_b64_e32 v[4:5], 0xaff
	v_cmp_gt_i64_e32 vcc, s[10:11], v[4:5]
	s_mov_b64 s[8:9], -1
	s_cbranch_vccnz .LBB0_2098
	s_ashr_i32 s8, s10, 31
	s_lshr_b32 s8, s8, 29
	s_add_i32 s8, s10, s8
	s_ashr_i32 s9, s8, 3
	s_and_b32 s8, s8, -8
	s_sub_i32 s8, s10, s8
	s_cmp_lt_i32 s8, 0
	s_movk_i32 s3, 0x161
	s_cselect_b32 s12, s3, 0x160
	s_mul_i32 s8, s8, s12
	s_add_i32 s8, s8, s9
	s_mul_hi_i32 s9, s8, 0x2e8ba2e9
	s_lshr_b32 s12, s9, 31
	s_ashr_i32 s9, s9, 5
	s_add_i32 s9, s9, s12
	s_lshl_b32 s12, s9, 2
	s_sub_i32 s13, 64, s12
	s_min_i32 s13, s13, 4
	s_abs_i32 s13, s13
	v_cvt_f32_u32_e32 v4, s13
	s_sub_i32 s15, 0, s13
	s_mulk_i32 s9, 0xb0
	s_sub_i32 s8, s8, s9
	v_rcp_iflag_f32_e32 v4, v4
	s_ashr_i32 s9, s8, 31
	s_abs_i32 s8, s8
	v_xor_b32_e32 v7, 1, v216
	v_mul_f32_e32 v4, 0x4f7ffffe, v4
	v_cvt_u32_f32_e32 v4, v4
	v_cmp_lt_i32_e32 vcc, v7, v217
	v_readfirstlane_b32 s16, v4
	s_mul_i32 s15, s15, s16
	s_mul_hi_u32 s15, s16, s15
	s_add_i32 s16, s16, s15
	s_mul_hi_u32 s15, s8, s16
	s_mul_i32 s15, s15, s13
	s_sub_i32 s8, s8, s15
	s_sub_i32 s15, s8, s13
	s_cmp_ge_u32 s8, s13
	s_cselect_b32 s8, s15, s8
	s_sub_i32 s15, s8, s13
	s_cmp_ge_u32 s8, s13
	s_cselect_b32 s8, s15, s8
	s_xor_b32 s8, s8, s9
	s_sub_i32 s8, s8, s9
	s_add_i32 s12, s12, s8
	s_cmp_eq_u32 s12, s86
	s_cbranch_scc1 .Lmy_rsame_3
	s_mov_b32 s86, s12
	v_lshl_add_u32 v4, s12, 8, v6
	v_ashrrev_i32_e32 v5, 31, v4
	s_waitcnt lgkmcnt(0)
	v_lshlrev_b64 v[8:9], 7, v[4:5]
	v_lshl_add_u64 v[248:249], v[4:5], 2, s[4:5]
	global_load_dword v250, v[248:249], off
	v_lshl_add_u64 v[20:21], v[2:3], 0, v[8:9]
	global_load_dwordx4 v[8:11], v[20:21], off
	global_load_dwordx4 v[12:15], v[20:21], off offset:16
	global_load_dwordx4 v[16:19], v[20:21], off offset:32
	s_nop 0
	global_load_dwordx4 v[20:23], v[20:21], off offset:48
	v_cndmask_b32_e32 v24, v216, v7, vcc
	s_waitcnt vmcnt(0)
	v_add_f32_e32 v7, v8, v9
	v_add_f32_e32 v8, v10, v11
	v_add_f32_e32 v9, v12, v13
	v_add_f32_e32 v10, v14, v15
	v_add_f32_e32 v11, v16, v17
	v_add_f32_e32 v12, v18, v19
	v_add_f32_e32 v13, v20, v21
	v_add_f32_e32 v14, v22, v23
	v_add_f32_e32 v7, v7, v8
	v_add_f32_e32 v8, v9, v10
	v_add_f32_e32 v9, v11, v12
	v_add_f32_e32 v10, v13, v14
	v_add_f32_e32 v7, v7, v8
	v_add_f32_e32 v8, v9, v10
	v_add_f32_e32 v7, v7, v8
	v_lshlrev_b32_e32 v8, 2, v24
	ds_bpermute_b32 v8, v8, v7
	s_and_saveexec_b64 s[12:13], s[6:7]
	s_cbranch_execz .LBB0_2097
	s_waitcnt lgkmcnt(0)
	v_add_f32_e32 v7, v7, v8
	v_fmamk_f32 v7, v7, 0x3a000000, v156
	s_mov_b32 s3, 0xf800000
	v_cmp_gt_f32_e32 vcc, s3, v7
	v_mul_f32_e32 v8, 0x4f800000, v7
	s_nop 0
	v_cndmask_b32_e32 v7, v7, v8, vcc
	v_sqrt_f32_e32 v8, v7
	s_nop 0
	v_add_u32_e32 v9, -1, v8
	v_fma_f32 v10, -v9, v8, v7
	v_cmp_ge_f32_e64 s[8:9], 0, v10
	v_add_u32_e32 v10, 1, v8
	s_nop 0
	v_cndmask_b32_e64 v9, v8, v9, s[8:9]
	v_fma_f32 v8, -v10, v8, v7
	v_cmp_lt_f32_e64 s[8:9], 0, v8
	s_nop 1
	v_cndmask_b32_e64 v8, v9, v10, s[8:9]
	v_mul_f32_e32 v9, 0x37800000, v8
	v_cndmask_b32_e32 v8, v8, v9, vcc
	v_cmp_class_f32_e32 vcc, v7, v157
	s_nop 1
	v_cndmask_b32_e32 v7, v8, v7, vcc
	v_div_scale_f32 v8, s[8:9], v7, v7, 1.0
	v_rcp_f32_e32 v9, v8
	s_nop 0
	v_fma_f32 v10, -v8, v9, 1.0
	v_fmac_f32_e32 v9, v10, v9
	v_div_scale_f32 v10, vcc, 1.0, v7, 1.0
	v_mul_f32_e32 v11, v10, v9
	v_fma_f32 v12, -v8, v11, v10
	v_fmac_f32_e32 v11, v12, v9
	v_fma_f32 v8, -v8, v11, v10
	v_div_fmas_f32 v8, v8, v9, v11
	v_div_fixup_f32 v7, v8, v7, 1.0
	s_waitcnt vmcnt(0)
	v_mul_f32_e32 v4, v7, v250
	v_mov_b32_e32 v100, v4
	ds_write_b32 v0, v4
	s_branch .LBB0_2097
